# norm1/norm2 row loops: next row's x prefetched into spare registers while the current row is reduced and written
# baseline (speedup 1.0000x reference)
; __device__ __forceinline__ void st_bf4(bf16_t* p, const f32x4 v) { u32x2 w; w.x = cvt_pk_bf16(v[0], v[1]); w.y = cvt_pk_bf16(v[2], v[3]); *(u32x2*)p = w; }
; DI void norm_phase(const float* xp, const float* xs, const float* gvec, const float* MODL  , int sc_off, bf16_t* H, int tid,
;                    const float* P, int nparts, const float* pgate, float* X) {
;     const int lane = tid & 63, gw = blockIdx.x * 8 + (tid >> 6), NGW = gridDim.x * 8;
;     for (int it = gw; it < M; it += NGW) {
;         const int row = it < MS ? MP + it : it - MS;
;         const int bi = batch_of(row);
;         const float* xr = (row < MP ? xp : xs) + (size_t)row * 1024; const float* mr = MODL + (size_t)bi * NMOD;
;         f32x4 v[4]; float ss = 0.f;
; #pragma unroll
;         for (int j = 0; j < 4; ++j) v[j] = *(const f32x4*)(xr + 4 * lane + 256 * j);
;         if (row >= MP && nparts > 0) {
;             f32x4 s[4];
; #pragma unroll
;             for (int j = 0; j < 4; ++j) s[j] = (f32x4){0.f, 0.f, 0.f, 0.f};
;             for (int p = 0; p < nparts; ++p) { const float* pr = P + ((size_t)p * 512 + (row - MP)) * 1024 + 4 * lane;
; #pragma unroll
;                 for (int j = 0; j < 4; ++j) s[j] += *(const f32x4*)(pr + 256 * j); }
; #pragma unroll
;             for (int j = 0; j < 4; ++j) { v[j] += *(const f32x4*)(pgate + (size_t)bi * NMOD + 4 * lane + 256 * j) * s[j]; *(f32x4*)(X + (size_t)row * 1024 + 4 * lane + 256 * j) = v[j]; }
;         }
; #pragma unroll
;         for (int j = 0; j < 4; ++j) ss += v[j][0] * v[j][0] + v[j][1] * v[j][1] + v[j][2] * v[j][2] + v[j][3] * v[j][3];
;         const float r = rsqrtf(wave_sum(ss, lane) * (1.f / 1024.f) + 1e-6f);
;         if (H) {
; #pragma unroll
;             for (int j = 0; j < 4; ++j) { const int c = 4 * lane + 256 * j; const f32x4 g = *(const f32x4*)(gvec + c), sh = *(const f32x4*)(mr + c), sc = *(const f32x4*)(mr + sc_off + c);
;                 st_bf4(H + (size_t)row * 1024 + c, v[j] * r * g * (1.f + sc) + sh); }
;         } else {
; #pragma unroll
;             for (int j = 0; j < 4; ++j) { const int c = 4 * lane + 256 * j; *(f32x4*)(X + (size_t)row * 1024 + c) = v[j] * r * *(const f32x4*)(gvec + c); }
;         }
;     }
.LBB0_225:
	v_ashrrev_i32_e32 v0, 6, v194
	v_add_u32_e32 v16, s83, v0
	s_movk_i32 s2, 0x4200
	v_cmp_gt_i32_e32 vcc, s2, v16
	s_and_saveexec_b64 s[2:3], vcc
	s_cbranch_execz .LBB0_230
	v_readlane_b32 s4, v254, 29
	v_readlane_b32 s5, v254, 30
	s_lshl_b64 s[4:5], s[4:5], 2
	s_load_dwordx2 s[8:9], s[34:35], 0x50
	s_add_u32 s6, s36, s4
	s_addc_u32 s7, s37, s5
	v_readlane_b32 s10, v254, 33
	s_add_u32 s4, s6, 0x3000
	v_readlane_b32 s11, v254, 34
	v_lshlrev_b32_e32 v1, 2, v194
	s_addc_u32 s5, s7, 0
	s_lshl_b64 s[10:11], s[10:11], 2
	v_and_b32_e32 v0, 0xfc, v1
	s_waitcnt lgkmcnt(0)
	s_add_u32 s8, s8, s10
	v_lshlrev_b32_e32 v2, 2, v0
	v_mov_b32_e32 v3, v97
	s_addc_u32 s9, s9, s11
	v_lshl_add_u64 v[4:5], s[26:27], 0, v[2:3]
	s_mov_b64 s[10:11], 0x13f00000
	v_lshl_add_u64 v[18:19], v[4:5], 0, s[10:11]
	v_lshl_add_u64 v[4:5], s[6:7], 0, v[2:3]
	s_mov_b64 s[6:7], 0x2000
	v_lshl_add_u64 v[20:21], v[4:5], 0, s[6:7]
	v_bfrev_b32_e32 v4, 0.5
	s_movk_i32 s6, 0x80
	v_lshl_add_u64 v[22:23], s[24:25], 0, v[2:3]
	v_bitop3_b32 v54, v1, 4, v4 bitop3:0x6c
	v_bitop3_b32 v55, v1, 8, v4 bitop3:0x6c
	v_bitop3_b32 v56, v1, 16, v4 bitop3:0x6c
	v_bitop3_b32 v57, v1, 32, v4 bitop3:0x6c
	v_bitop3_b32 v58, v1, 64, v4 bitop3:0x6c
	v_bitop3_b32 v59, v1, s6, v4 bitop3:0x6c
	v_lshl_add_u64 v[24:25], s[8:9], 0, v[2:3]
	v_or_b32_e32 v2, 0x100, v0
	v_or_b32_e32 v4, 0x200, v0
	v_or_b32_e32 v6, 0x300, v0
	v_lshlrev_b32_e32 v8, 1, v0
	v_mov_b32_e32 v9, v97
	v_lshl_add_u64 v[26:27], s[88:89], 0, v[8:9]
	v_ashrrev_i32_e32 v17, 31, v16
	s_mov_b64 s[8:9], 0
	v_lshlrev_b32_e32 v96, 2, v0
	v_lshlrev_b32_e32 v28, 2, v2
	v_lshlrev_b32_e32 v30, 2, v4
	v_lshlrev_b32_e32 v32, 2, v6
	s_mov_b32 s101, 0
	s_branch .LBB0_228
.LBB0_227:
	s_or_b64 exec, exec, s[6:7]
	s_waitcnt vmcnt(0)
	v_pk_mul_f32 v[50:51], v[12:13], v[12:13]
	v_pk_mul_f32 v[52:53], v[8:9], v[8:9]
	v_pk_mul_f32 v[46:47], v[14:15], v[14:15]
	v_pk_mul_f32 v[48:49], v[10:11], v[10:11]
	v_mov_b32_e32 v60, v50
	v_mov_b32_e32 v61, v52
	v_mov_b32_e32 v52, v51
	v_pk_add_f32 v[50:51], v[60:61], v[52:53]
	v_mov_b32_e32 v52, v46
	v_mov_b32_e32 v53, v48
	v_pk_mul_f32 v[42:43], v[0:1], v[0:1]
	v_pk_mul_f32 v[44:45], v[4:5], v[4:5]
	v_pk_add_f32 v[50:51], v[52:53], v[50:51]
	v_mov_b32_e32 v48, v47
	v_lshl_add_u64 v[40:41], v[36:37], 2, s[4:5]
	v_pk_mul_f32 v[36:37], v[2:3], v[2:3]
	v_pk_mul_f32 v[38:39], v[6:7], v[6:7]
	v_pk_add_f32 v[46:47], v[48:49], v[50:51]
	v_mov_b32_e32 v48, v42
	v_mov_b32_e32 v49, v44
	v_mov_b32_e32 v44, v43
	v_pk_add_f32 v[42:43], v[48:49], v[44:45]
	v_mov_b32_e32 v44, v36
	v_mov_b32_e32 v45, v38
	v_pk_add_f32 v[42:43], v[44:45], v[42:43]
	v_mov_b32_e32 v38, v37
	s_mov_b64 s[6:7], 0x1000
	v_pk_add_f32 v[36:37], v[38:39], v[42:43]
	v_lshl_add_u64 v[38:39], v[40:41], 0, s[6:7]
	v_lshl_add_u64 v[40:41], v[40:41], 0, v[96:97]
	v_lshl_add_u64 v[50:51], v[38:39], 0, v[96:97]
	v_add_f32_e32 v29, v46, v47
	global_load_dwordx4 v[42:45], v[24:25], off
	global_load_dwordx4 v[46:49], v[40:41], off
	v_add_f32_e32 v29, v37, v29
	global_load_dwordx4 v[50:53], v[50:51], off
	global_load_dwordx4 v[198:201], v[24:25], off offset:1024
	global_load_dwordx4 v[210:213], v[40:41], off offset:1024
	v_mov_b32_e32 v234, v28
	v_mov_b32_e32 v235, v97
	v_lshl_add_u64 v[234:235], v[38:39], 0, v[234:235]
	global_load_dwordx4 v[222:225], v[234:235], off
	global_load_dwordx4 v[202:205], v[24:25], off offset:2048
	global_load_dwordx4 v[214:217], v[40:41], off offset:2048
	v_mov_b32_e32 v236, v30
	v_mov_b32_e32 v237, v97
	v_lshl_add_u64 v[236:237], v[38:39], 0, v[236:237]
	global_load_dwordx4 v[226:229], v[236:237], off
	global_load_dwordx4 v[206:209], v[24:25], off offset:3072
	global_load_dwordx4 v[218:221], v[40:41], off offset:3072
	v_mov_b32_e32 v238, v32
	v_mov_b32_e32 v239, v97
	v_lshl_add_u64 v[238:239], v[38:39], 0, v[238:239]
	global_load_dwordx4 v[230:233], v[238:239], off
	v_add_f32_e32 v29, v36, v29
	ds_bpermute_b32 v31, v54, v29
	v_lshl_add_u64 v[34:35], v[34:35], 1, v[26:27]
	v_mov_b32_e32 v33, v97
	v_lshl_add_u64 v[16:17], v[16:17], 0, s[48:49]
	v_min_i32_e32 v116, 0x41ff, v16
	v_add_u32_e32 v116, 0xfffffe00, v116
	v_lshlrev_b32_e32 v116, 12, v116
	v_mov_b32_e32 v117, v97
	v_lshl_add_u64 v[116:117], s[24:25], 0, v[116:117]
	v_lshl_add_u64 v[116:117], v[116:117], 0, v[96:97]
	global_load_dwordx4 v[100:103], v[116:117], off
	global_load_dwordx4 v[104:107], v[116:117], off offset:1024
	global_load_dwordx4 v[108:111], v[116:117], off offset:2048
	global_load_dwordx4 v[112:115], v[116:117], off offset:3072
	s_movk_i32 s6, 0x41ff
	s_waitcnt lgkmcnt(0)
	v_add_f32_e32 v29, v29, v31
	ds_bpermute_b32 v31, v55, v29
	s_waitcnt lgkmcnt(0)
	v_add_f32_e32 v29, v29, v31
	ds_bpermute_b32 v31, v56, v29
	s_waitcnt lgkmcnt(0)
	v_add_f32_e32 v29, v29, v31
	ds_bpermute_b32 v31, v57, v29
	s_waitcnt lgkmcnt(0)
	v_add_f32_e32 v29, v29, v31
	ds_bpermute_b32 v31, v58, v29
	s_waitcnt lgkmcnt(0)
	v_add_f32_e32 v29, v29, v31
	ds_bpermute_b32 v31, v59, v29
	s_waitcnt lgkmcnt(0)
	v_add_f32_e32 v29, v29, v31
	v_mov_b32_e32 v31, 0x358637bd
	v_fmamk_f32 v29, v29, 0x3a800000, v31
	v_cmp_gt_f32_e32 vcc, s42, v29
	v_mul_f32_e32 v31, 0x4b800000, v29
	s_nop 0
	v_cndmask_b32_e32 v29, v29, v31, vcc
	v_rsq_f32_e32 v29, v29
	s_nop 0
	v_mul_f32_e32 v31, 0x45800000, v29
	v_cndmask_b32_e32 v36, v29, v31, vcc
	v_pk_mul_f32 v[14:15], v[14:15], v[36:37] op_sel_hi:[1,0]
	v_pk_mul_f32 v[12:13], v[12:13], v[36:37] op_sel_hi:[1,0]
	v_mov_b32_e32 v29, v97
	v_pk_mul_f32 v[10:11], v[10:11], v[36:37] op_sel_hi:[1,0]
	v_pk_mul_f32 v[8:9], v[8:9], v[36:37] op_sel_hi:[1,0]
	v_mov_b32_e32 v31, v97
	v_pk_mul_f32 v[6:7], v[6:7], v[36:37] op_sel_hi:[1,0]
	v_pk_mul_f32 v[4:5], v[4:5], v[36:37] op_sel_hi:[1,0]
	v_pk_mul_f32 v[2:3], v[2:3], v[36:37] op_sel_hi:[1,0]
	v_pk_mul_f32 v[0:1], v[0:1], v[36:37] op_sel_hi:[1,0]
	v_cmp_lt_i32_e32 vcc, s6, v16
	s_or_b64 s[8:9], vcc, s[8:9]
	s_waitcnt vmcnt(13)
; __device__ __forceinline__ void st_bf4(bf16_t* p, const f32x4 v) { u32x2 w; w.x = cvt_pk_bf16(v[0], v[1]); w.y = cvt_pk_bf16(v[2], v[3]); *(u32x2*)p = w; }
; DI void norm_phase(const float* xp, const float* xs, const float* gvec, const float* MODL  , int sc_off, bf16_t* H, int tid,
;                    const float* P, int nparts, const float* pgate, float* X) {
;     ...
;     for (int it = gw; it < M; it += NGW) {
;         const int row = it < MS ? MP + it : it - MS;
;         const int bi = batch_of(row);
;         const float* xr = (row < MP ? xp : xs) + (size_t)row * 1024; const float* mr = MODL + (size_t)bi * NMOD;
;         f32x4 v[4]; float ss = 0.f;
; #pragma unroll
;         for (int j = 0; j < 4; ++j) v[j] = *(const f32x4*)(xr + 4 * lane + 256 * j);
;         if (row >= MP && nparts > 0) {
;             f32x4 s[4];
; #pragma unroll
;             for (int j = 0; j < 4; ++j) s[j] = (f32x4){0.f, 0.f, 0.f, 0.f};
;             for (int p = 0; p < nparts; ++p) { const float* pr = P + ((size_t)p * 512 + (row - MP)) * 1024 + 4 * lane;
; #pragma unroll
;                 for (int j = 0; j < 4; ++j) s[j] += *(const f32x4*)(pr + 256 * j); }
; #pragma unroll
;             for (int j = 0; j < 4; ++j) { v[j] += *(const f32x4*)(pgate + (size_t)bi * NMOD + 4 * lane + 256 * j) * s[j]; *(f32x4*)(X + (size_t)row * 1024 + 4 * lane + 256 * j) = v[j]; }
;         }
; #pragma unroll
;         for (int j = 0; j < 4; ++j) ss += v[j][0] * v[j][0] + v[j][1] * v[j][1] + v[j][2] * v[j][2] + v[j][3] * v[j][3];
;         const float r = rsqrtf(wave_sum(ss, lane) * (1.f / 1024.f) + 1e-6f);
;         if (H) {
; #pragma unroll
;             for (int j = 0; j < 4; ++j) { const int c = 4 * lane + 256 * j; const f32x4 g = *(const f32x4*)(gvec + c), sh = *(const f32x4*)(mr + c), sc = *(const f32x4*)(mr + sc_off + c);
;                 st_bf4(H + (size_t)row * 1024 + c, v[j] * r * g * (1.f + sc) + sh); }
;         } else {
; #pragma unroll
;             for (int j = 0; j < 4; ++j) { const int c = 4 * lane + 256 * j; *(f32x4*)(X + (size_t)row * 1024 + c) = v[j] * r * *(const f32x4*)(gvec + c); }
;         }
;     }
	v_pk_mul_f32 v[12:13], v[42:43], v[12:13]
	v_pk_mul_f32 v[14:15], v[44:45], v[14:15]
	v_pk_add_f32 v[50:51], v[50:51], 1.0 op_sel_hi:[1,0]
	v_pk_add_f32 v[52:53], v[52:53], 1.0 op_sel_hi:[1,0]
	v_pk_fma_f32 v[12:13], v[50:51], v[12:13], v[46:47]
	v_pk_fma_f32 v[14:15], v[52:53], v[14:15], v[48:49]
	v_cvt_pk_bf16_f32 v12, v12, v13
	v_cvt_pk_bf16_f32 v13, v14, v15
	global_store_dwordx2 v[34:35], v[12:13], off
	s_waitcnt vmcnt(11)
	v_pk_mul_f32 v[8:9], v[198:199], v[8:9]
	v_pk_mul_f32 v[10:11], v[200:201], v[10:11]
	v_pk_add_f32 v[222:223], v[222:223], 1.0 op_sel_hi:[1,0]
	v_pk_add_f32 v[224:225], v[224:225], 1.0 op_sel_hi:[1,0]
	v_pk_fma_f32 v[8:9], v[222:223], v[8:9], v[210:211]
	v_pk_fma_f32 v[10:11], v[224:225], v[10:11], v[212:213]
	v_cvt_pk_bf16_f32 v8, v8, v9
	v_cvt_pk_bf16_f32 v9, v10, v11
	global_store_dwordx2 v[34:35], v[8:9], off offset:512
	s_waitcnt vmcnt(9)
	v_pk_mul_f32 v[4:5], v[202:203], v[4:5]
	v_pk_mul_f32 v[6:7], v[204:205], v[6:7]
	v_pk_add_f32 v[226:227], v[226:227], 1.0 op_sel_hi:[1,0]
	v_pk_add_f32 v[228:229], v[228:229], 1.0 op_sel_hi:[1,0]
	v_pk_fma_f32 v[4:5], v[226:227], v[4:5], v[214:215]
	v_pk_fma_f32 v[6:7], v[228:229], v[6:7], v[216:217]
	v_cvt_pk_bf16_f32 v4, v4, v5
	v_cvt_pk_bf16_f32 v5, v6, v7
	global_store_dwordx2 v[34:35], v[4:5], off offset:1024
	s_waitcnt vmcnt(7)
	v_pk_mul_f32 v[0:1], v[206:207], v[0:1]
	v_pk_mul_f32 v[2:3], v[208:209], v[2:3]
	v_pk_add_f32 v[230:231], v[230:231], 1.0 op_sel_hi:[1,0]
	v_pk_add_f32 v[232:233], v[232:233], 1.0 op_sel_hi:[1,0]
	v_pk_fma_f32 v[0:1], v[230:231], v[0:1], v[218:219]
	v_pk_fma_f32 v[2:3], v[232:233], v[2:3], v[220:221]
	v_cvt_pk_bf16_f32 v0, v0, v1
	v_cvt_pk_bf16_f32 v1, v2, v3
	global_store_dwordx2 v[34:35], v[0:1], off offset:1536
	s_andn2_b64 exec, exec, s[8:9]
	s_cbranch_execz .LBB0_230
.LBB0_228:
	v_cmp_gt_i32_e32 vcc, s96, v16
	v_mov_b32_e32 v0, 0xfffffe00
	v_mov_b32_e32 v1, 0x4000
	v_cndmask_b32_e32 v0, v0, v1, vcc
	v_add_u32_e32 v29, v0, v16
	v_add_u32_e32 v38, 0xffffc000, v29
	v_lshrrev_b32_e32 v2, 2, v38
	s_movk_i32 s6, 0x4000
	v_readlane_b32 s10, v254, 25
	v_ashrrev_i32_e32 v1, 11, v29
	v_add_u32_e32 v2, 8, v2
	v_cmp_gt_i32_e64 s[6:7], s6, v29
	v_readlane_b32 s11, v254, 26
	s_nop 0
	v_cndmask_b32_e64 v31, v2, v1, s[6:7]
	v_mov_b32_e32 v1, s11
	v_mov_b32_e32 v2, s25
	v_cndmask_b32_e64 v3, v1, v2, s[6:7]
	v_mov_b32_e32 v1, s10
	v_mov_b32_e32 v2, s24
	v_cndmask_b32_e64 v2, v1, v2, s[6:7]
	v_cndmask_b32_e64 v1, -1, 0, vcc
	v_lshl_add_u64 v[34:35], v[16:17], 0, v[0:1]
	v_lshlrev_b64 v[0:1], 12, v[34:35]
	v_lshl_add_u64 v[0:1], v[2:3], 0, v[0:1]
	v_lshl_add_u64 v[0:1], v[0:1], 0, v[96:97]
	s_cmp_lg_u32 s101, 0
	s_cbranch_scc1 .Lnp_pf_n2
	global_load_dwordx4 v[12:15], v[0:1], off
	global_load_dwordx4 v[8:11], v[0:1], off offset:1024
	global_load_dwordx4 v[4:7], v[0:1], off offset:2048
	s_nop 0
	global_load_dwordx4 v[0:3], v[0:1], off offset:3072
	s_branch .Lnp_go_n2
.Lnp_pf_n2:
	s_waitcnt vmcnt(4)
	v_mov_b32_e32 v12, v100
	v_mov_b32_e32 v13, v101
	v_mov_b32_e32 v14, v102
	v_mov_b32_e32 v15, v103
	v_mov_b32_e32 v8, v104
	v_mov_b32_e32 v9, v105
	v_mov_b32_e32 v10, v106
	v_mov_b32_e32 v11, v107
	v_mov_b32_e32 v4, v108
	v_mov_b32_e32 v5, v109
	v_mov_b32_e32 v6, v110
	v_mov_b32_e32 v7, v111
	v_mov_b32_e32 v0, v112
	v_mov_b32_e32 v1, v113
	v_mov_b32_e32 v2, v114
	v_mov_b32_e32 v3, v115
.Lnp_go_n2:
	s_mov_b32 s101, 1
	s_movk_i32 s6, 0x6000
	v_mad_i64_i32 v[36:37], s[6:7], v31, s6, 0
	s_movk_i32 s6, 0x3fff
	v_lshlrev_b64 v[34:35], 10, v[34:35]
	v_cmp_lt_i32_e32 vcc, s6, v29
	s_and_saveexec_b64 s[6:7], vcc
	s_cbranch_execz .LBB0_227
	v_mov_b32_e32 v39, v97
	v_lshlrev_b64 v[38:39], 12, v[38:39]
	v_lshl_add_u64 v[38:39], v[18:19], 0, v[38:39]
	v_mov_b64_e32 v[132:133], v[38:39]
	v_lshl_add_u64 v[164:165], v[36:37], 2, v[20:21]
	v_lshl_add_u64 v[178:179], v[34:35], 2, v[22:23]
	global_load_dwordx4 v[170:173], v[164:165], off
	global_load_dwordx4 v[174:177], v[164:165], off offset:1024
	global_load_dwordx4 v[190:193], v[164:165], off offset:2048
	global_load_dwordx4 v[250:253], v[164:165], off offset:3072
	global_load_dwordx4 v[198:201], v[132:133], off
	global_load_dwordx4 v[202:205], v[132:133], off offset:1024
	global_load_dwordx4 v[206:209], v[132:133], off offset:2048
	global_load_dwordx4 v[210:213], v[132:133], off offset:3072
	v_add_co_u32_e32 v132, vcc, 0x200000, v132
	s_nop 1
	v_addc_co_u32_e32 v133, vcc, 0, v133, vcc
	global_load_dwordx4 v[214:217], v[132:133], off
	global_load_dwordx4 v[218:221], v[132:133], off offset:1024
	global_load_dwordx4 v[222:225], v[132:133], off offset:2048
	global_load_dwordx4 v[226:229], v[132:133], off offset:3072
	v_add_co_u32_e32 v132, vcc, 0x200000, v132
	s_nop 1
	v_addc_co_u32_e32 v133, vcc, 0, v133, vcc
	global_load_dwordx4 v[230:233], v[132:133], off
	global_load_dwordx4 v[234:237], v[132:133], off offset:1024
	global_load_dwordx4 v[238:241], v[132:133], off offset:2048
	global_load_dwordx4 v[242:245], v[132:133], off offset:3072
	v_add_co_u32_e32 v132, vcc, 0x200000, v132
	s_nop 1
	v_addc_co_u32_e32 v133, vcc, 0, v133, vcc
	global_load_dwordx4 v[246:249], v[132:133], off
	global_load_dwordx4 v[148:151], v[132:133], off offset:1024
	global_load_dwordx4 v[152:155], v[132:133], off offset:2048
	global_load_dwordx4 v[156:159], v[132:133], off offset:3072
	v_add_co_u32_e32 v132, vcc, 0x200000, v132
	s_nop 1
	v_addc_co_u32_e32 v133, vcc, 0, v133, vcc
	global_load_dwordx4 v[160:163], v[132:133], off
	global_load_dwordx4 v[182:185], v[132:133], off offset:1024
	global_load_dwordx4 v[186:189], v[132:133], off offset:2048
	s_waitcnt vmcnt(18)
; DI void norm_phase(const float* xp, const float* xs, const float* gvec, const float* MODL  , int sc_off, bf16_t* H, int tid,
;                    const float* P, int nparts, const float* pgate, float* X) {
;     ...
;         if (row >= MP && nparts > 0) {
;             f32x4 s[4];
; #pragma unroll
;             for (int j = 0; j < 4; ++j) s[j] = (f32x4){0.f, 0.f, 0.f, 0.f};
;             for (int p = 0; p < nparts; ++p) { const float* pr = P + ((size_t)p * 512 + (row - MP)) * 1024 + 4 * lane;
; #pragma unroll
;                 for (int j = 0; j < 4; ++j) s[j] += *(const f32x4*)(pr + 256 * j); }
; #pragma unroll
;             for (int j = 0; j < 4; ++j) { v[j] += *(const f32x4*)(pgate + (size_t)bi * NMOD + 4 * lane + 256 * j) * s[j]; *(f32x4*)(X + (size_t)row * 1024 + 4 * lane + 256 * j) = v[j]; }
;         }
	v_pk_add_f32 v[126:127], v[200:201], 0 op_sel_hi:[1,0]
	v_pk_add_f32 v[124:125], v[198:199], 0 op_sel_hi:[1,0]
	global_load_dwordx4 v[198:201], v[132:133], off offset:3072
	s_waitcnt vmcnt(18)
	v_pk_add_f32 v[130:131], v[204:205], 0 op_sel_hi:[1,0]
	v_pk_add_f32 v[128:129], v[202:203], 0 op_sel_hi:[1,0]
	v_add_co_u32_e32 v132, vcc, 0x200000, v132
	s_nop 1
	v_addc_co_u32_e32 v133, vcc, 0, v133, vcc
	global_load_dwordx4 v[202:205], v[132:133], off
	s_waitcnt vmcnt(18)
	v_pk_add_f32 v[140:141], v[208:209], 0 op_sel_hi:[1,0]
	v_pk_add_f32 v[138:139], v[206:207], 0 op_sel_hi:[1,0]
	global_load_dwordx4 v[206:209], v[132:133], off offset:1024
	s_waitcnt vmcnt(18)
	v_pk_add_f32 v[144:145], v[212:213], 0 op_sel_hi:[1,0]
	v_pk_add_f32 v[142:143], v[210:211], 0 op_sel_hi:[1,0]
	global_load_dwordx4 v[210:213], v[132:133], off offset:2048
	s_waitcnt vmcnt(18)
	v_pk_add_f32 v[126:127], v[126:127], v[216:217]
	v_pk_add_f32 v[124:125], v[124:125], v[214:215]
	global_load_dwordx4 v[214:217], v[132:133], off offset:3072
	s_waitcnt vmcnt(18)
	v_pk_add_f32 v[130:131], v[130:131], v[220:221]
	v_pk_add_f32 v[128:129], v[128:129], v[218:219]
	v_add_co_u32_e32 v132, vcc, 0x200000, v132
	s_nop 1
	v_addc_co_u32_e32 v133, vcc, 0, v133, vcc
	global_load_dwordx4 v[218:221], v[132:133], off
	s_waitcnt vmcnt(18)
	v_pk_add_f32 v[140:141], v[140:141], v[224:225]
	v_pk_add_f32 v[138:139], v[138:139], v[222:223]
	global_load_dwordx4 v[222:225], v[132:133], off offset:1024
	s_waitcnt vmcnt(18)
	v_pk_add_f32 v[144:145], v[144:145], v[228:229]
	v_pk_add_f32 v[142:143], v[142:143], v[226:227]
	global_load_dwordx4 v[226:229], v[132:133], off offset:2048
	s_waitcnt vmcnt(18)
	v_pk_add_f32 v[126:127], v[126:127], v[232:233]
	v_pk_add_f32 v[124:125], v[124:125], v[230:231]
	global_load_dwordx4 v[230:233], v[132:133], off offset:3072
	s_waitcnt vmcnt(18)
	v_pk_add_f32 v[130:131], v[130:131], v[236:237]
	v_pk_add_f32 v[128:129], v[128:129], v[234:235]
	v_add_co_u32_e32 v132, vcc, 0x200000, v132
	s_nop 1
	v_addc_co_u32_e32 v133, vcc, 0, v133, vcc
	global_load_dwordx4 v[234:237], v[132:133], off
	s_waitcnt vmcnt(18)
	v_pk_add_f32 v[140:141], v[140:141], v[240:241]
	v_pk_add_f32 v[138:139], v[138:139], v[238:239]
	global_load_dwordx4 v[238:241], v[132:133], off offset:1024
	s_waitcnt vmcnt(18)
	v_pk_add_f32 v[144:145], v[144:145], v[244:245]
	v_pk_add_f32 v[142:143], v[142:143], v[242:243]
	global_load_dwordx4 v[242:245], v[132:133], off offset:2048
	s_waitcnt vmcnt(18)
	v_pk_add_f32 v[126:127], v[126:127], v[248:249]
	v_pk_add_f32 v[124:125], v[124:125], v[246:247]
	global_load_dwordx4 v[246:249], v[132:133], off offset:3072
	s_waitcnt vmcnt(18)
	v_pk_add_f32 v[130:131], v[130:131], v[150:151]
	v_pk_add_f32 v[128:129], v[128:129], v[148:149]
	s_waitcnt vmcnt(17)
	v_pk_add_f32 v[140:141], v[140:141], v[154:155]
	v_pk_add_f32 v[138:139], v[138:139], v[152:153]
	s_waitcnt vmcnt(16)
	v_pk_add_f32 v[144:145], v[144:145], v[158:159]
	v_pk_add_f32 v[142:143], v[142:143], v[156:157]
	s_waitcnt vmcnt(15)
	v_pk_add_f32 v[126:127], v[126:127], v[162:163]
	v_pk_add_f32 v[124:125], v[124:125], v[160:161]
	s_waitcnt vmcnt(14)
	v_pk_add_f32 v[130:131], v[130:131], v[184:185]
	v_pk_add_f32 v[128:129], v[128:129], v[182:183]
	s_waitcnt vmcnt(13)
	v_pk_add_f32 v[140:141], v[140:141], v[188:189]
	v_pk_add_f32 v[138:139], v[138:139], v[186:187]
	s_waitcnt vmcnt(12)
	v_pk_add_f32 v[144:145], v[144:145], v[200:201]
	v_pk_add_f32 v[142:143], v[142:143], v[198:199]
	s_waitcnt vmcnt(11)
	v_pk_add_f32 v[126:127], v[126:127], v[204:205]
	v_pk_add_f32 v[124:125], v[124:125], v[202:203]
	s_waitcnt vmcnt(10)
	v_pk_add_f32 v[130:131], v[130:131], v[208:209]
	v_pk_add_f32 v[128:129], v[128:129], v[206:207]
	s_waitcnt vmcnt(9)
	v_pk_add_f32 v[140:141], v[140:141], v[212:213]
	v_pk_add_f32 v[138:139], v[138:139], v[210:211]
	s_waitcnt vmcnt(8)
	v_pk_add_f32 v[144:145], v[144:145], v[216:217]
	v_pk_add_f32 v[142:143], v[142:143], v[214:215]
	s_waitcnt vmcnt(7)
	v_pk_add_f32 v[126:127], v[126:127], v[220:221]
	v_pk_add_f32 v[124:125], v[124:125], v[218:219]
	s_waitcnt vmcnt(6)
	v_pk_add_f32 v[130:131], v[130:131], v[224:225]
	v_pk_add_f32 v[128:129], v[128:129], v[222:223]
	s_waitcnt vmcnt(5)
	v_pk_add_f32 v[140:141], v[140:141], v[228:229]
	v_pk_add_f32 v[138:139], v[138:139], v[226:227]
	s_waitcnt vmcnt(4)
	v_pk_add_f32 v[144:145], v[144:145], v[232:233]
	v_pk_add_f32 v[142:143], v[142:143], v[230:231]
	s_waitcnt vmcnt(3)
	v_pk_add_f32 v[126:127], v[126:127], v[236:237]
	v_pk_add_f32 v[124:125], v[124:125], v[234:235]
	s_waitcnt vmcnt(2)
	v_pk_add_f32 v[130:131], v[130:131], v[240:241]
	v_pk_add_f32 v[128:129], v[128:129], v[238:239]
	s_waitcnt vmcnt(1)
	v_pk_add_f32 v[140:141], v[140:141], v[244:245]
	v_pk_add_f32 v[138:139], v[138:139], v[242:243]
	s_waitcnt vmcnt(0)
	v_pk_add_f32 v[144:145], v[144:145], v[248:249]
	v_pk_add_f32 v[142:143], v[142:143], v[246:247]
	v_pk_fma_f32 v[14:15], v[126:127], v[172:173], v[14:15]
	v_pk_fma_f32 v[12:13], v[124:125], v[170:171], v[12:13]
	global_store_dwordx4 v[178:179], v[12:15], off
	v_pk_fma_f32 v[10:11], v[130:131], v[176:177], v[10:11]
	v_pk_fma_f32 v[8:9], v[128:129], v[174:175], v[8:9]
	global_store_dwordx4 v[178:179], v[8:11], off offset:1024
	v_pk_fma_f32 v[6:7], v[140:141], v[192:193], v[6:7]
	v_pk_fma_f32 v[4:5], v[138:139], v[190:191], v[4:5]
	global_store_dwordx4 v[178:179], v[4:7], off offset:2048
	v_pk_fma_f32 v[2:3], v[144:145], v[252:253], v[2:3]
	v_pk_fma_f32 v[0:1], v[142:143], v[250:251], v[0:1]
	global_store_dwordx4 v[178:179], v[0:3], off offset:3072
	s_branch .LBB0_227

; DI void norm_phase(const float* xp, const float* xs, const float* gvec, const float* MODL  , int sc_off, bf16_t* H, int tid,
;                    const float* P, int nparts, const float* pgate, float* X) {
;     const int lane = tid & 63, gw = blockIdx.x * 8 + (tid >> 6), NGW = gridDim.x * 8;
;     for (int it = gw; it < M; it += NGW) {
;         const int row = it < MS ? MP + it : it - MS;
;         const int bi = batch_of(row);
;         const float* xr = (row < MP ? xp : xs) + (size_t)row * 1024; const float* mr = MODL + (size_t)bi * NMOD;
;         f32x4 v[4]; float ss = 0.f;
; #pragma unroll
;         for (int j = 0; j < 4; ++j) v[j] = *(const f32x4*)(xr + 4 * lane + 256 * j);
; __global__ void __launch_bounds__(512, 2) mega(Args a_unused) {
;     ...
;             if (k == 0) norm_phase(xp, xs, a->in[9] + l * 1024, MOD + l * 6144, 1024, H, tid, (const float*)(ws + WS_DYY), l == 0 ? 0 : 22, MOD + (l - 1) * 6144 + 5120, X);
.LBB0_1949:
	s_and_b64 vcc, exec, s[0:1]
	s_cbranch_vccz .LBB0_1956
	v_ashrrev_i32_e32 v0, 6, v194
	v_add_u32_e32 v20, s83, v0
	s_movk_i32 s0, 0x4200
	v_cmp_gt_i32_e32 vcc, s0, v20
	s_and_saveexec_b64 s[0:1], vcc
	v_readlane_b32 s10, v254, 23
	v_readlane_b32 s12, v254, 25
	v_readlane_b32 s11, v254, 24
	v_readlane_b32 s13, v254, 26
	s_cbranch_execz .LBB0_1955
	v_readlane_b32 s4, v254, 29
	v_readlane_b32 s5, v254, 30
	s_lshl_b64 s[2:3], s[4:5], 2
	s_add_u32 s2, s36, s2
	s_addc_u32 s3, s37, s3
	s_addk_i32 s4, 0xe800
	s_load_dwordx2 s[6:7], s[34:35], 0x48
	s_ashr_i32 s5, s4, 31
	s_lshl_b64 s[4:5], s[4:5], 2
	v_readlane_b32 s8, v254, 33
	s_add_u32 s4, s36, s4
	v_readlane_b32 s9, v254, 34
	v_lshlrev_b32_e32 v1, 2, v194
	s_addc_u32 s5, s37, s5
	s_lshl_b64 s[8:9], s[8:9], 2
	v_and_b32_e32 v0, 0xfc, v1
	s_waitcnt lgkmcnt(0)
	s_add_u32 s6, s6, s8
	v_lshlrev_b32_e32 v2, 2, v0
	v_mov_b32_e32 v3, v97
	s_addc_u32 s7, s7, s9
	v_lshl_add_u64 v[4:5], s[26:27], 0, v[2:3]
	s_mov_b64 s[8:9], 0x10d00000
	v_lshl_add_u64 v[22:23], v[4:5], 0, s[8:9]
	v_lshl_add_u64 v[4:5], s[4:5], 0, v[2:3]
	s_mov_b64 s[4:5], 0x5000
	v_lshl_add_u64 v[24:25], v[4:5], 0, s[4:5]
	v_bfrev_b32_e32 v4, 0.5
	s_movk_i32 s4, 0x80
	v_lshl_add_u64 v[26:27], s[24:25], 0, v[2:3]
	v_bitop3_b32 v62, v1, 4, v4 bitop3:0x6c
	v_bitop3_b32 v63, v1, 8, v4 bitop3:0x6c
	v_bitop3_b32 v64, v1, 16, v4 bitop3:0x6c
	v_bitop3_b32 v65, v1, 32, v4 bitop3:0x6c
	v_bitop3_b32 v66, v1, 64, v4 bitop3:0x6c
	v_bitop3_b32 v67, v1, s4, v4 bitop3:0x6c
	v_lshl_add_u64 v[28:29], s[6:7], 0, v[2:3]
	v_or_b32_e32 v2, 0x100, v0
	v_or_b32_e32 v4, 0x200, v0
	v_or_b32_e32 v6, 0x300, v0
	v_lshlrev_b32_e32 v8, 1, v0
	v_mov_b32_e32 v9, v97
	v_lshl_add_u64 v[30:31], s[88:89], 0, v[8:9]
	v_ashrrev_i32_e32 v21, 31, v20
	s_mov_b64 s[4:5], 0
	v_lshlrev_b32_e32 v96, 2, v0
	v_lshlrev_b32_e32 v32, 2, v2
	v_lshlrev_b32_e32 v34, 2, v4
	v_lshlrev_b32_e32 v36, 2, v6
	s_mov_b32 s101, 0
	s_branch .LBB0_1953
; __device__ __forceinline__ void st_bf4(bf16_t* p, const f32x4 v) { u32x2 w; w.x = cvt_pk_bf16(v[0], v[1]); w.y = cvt_pk_bf16(v[2], v[3]); *(u32x2*)p = w; }
; DI void norm_phase(const float* xp, const float* xs, const float* gvec, const float* MODL  , int sc_off, bf16_t* H, int tid,
;                    const float* P, int nparts, const float* pgate, float* X) {
;     ...
;     for (int it = gw; it < M; it += NGW) {
;         const int row = it < MS ? MP + it : it - MS;
;         const int bi = batch_of(row);
;         const float* xr = (row < MP ? xp : xs) + (size_t)row * 1024; const float* mr = MODL + (size_t)bi * NMOD;
;         f32x4 v[4]; float ss = 0.f;
; #pragma unroll
;         for (int j = 0; j < 4; ++j) v[j] = *(const f32x4*)(xr + 4 * lane + 256 * j);
;         if (row >= MP && nparts > 0) {
;             f32x4 s[4];
; #pragma unroll
;             for (int j = 0; j < 4; ++j) s[j] = (f32x4){0.f, 0.f, 0.f, 0.f};
;             for (int p = 0; p < nparts; ++p) { const float* pr = P + ((size_t)p * 512 + (row - MP)) * 1024 + 4 * lane;
; #pragma unroll
;                 for (int j = 0; j < 4; ++j) s[j] += *(const f32x4*)(pr + 256 * j); }
; #pragma unroll
;             for (int j = 0; j < 4; ++j) { v[j] += *(const f32x4*)(pgate + (size_t)bi * NMOD + 4 * lane + 256 * j) * s[j]; *(f32x4*)(X + (size_t)row * 1024 + 4 * lane + 256 * j) = v[j]; }
;         }
; #pragma unroll
;         for (int j = 0; j < 4; ++j) ss += v[j][0] * v[j][0] + v[j][1] * v[j][1] + v[j][2] * v[j][2] + v[j][3] * v[j][3];
;         const float r = rsqrtf(wave_sum(ss, lane) * (1.f / 1024.f) + 1e-6f);
;         if (H) {
; #pragma unroll
;             for (int j = 0; j < 4; ++j) { const int c = 4 * lane + 256 * j; const f32x4 g = *(const f32x4*)(gvec + c), sh = *(const f32x4*)(mr + c), sc = *(const f32x4*)(mr + sc_off + c);
;                 st_bf4(H + (size_t)row * 1024 + c, v[j] * r * g * (1.f + sc) + sh); }
.LBB0_1952:
	s_or_b64 exec, exec, s[6:7]
	s_waitcnt vmcnt(0)
	v_pk_mul_f32 v[50:51], v[12:13], v[12:13]
	v_pk_mul_f32 v[52:53], v[8:9], v[8:9]
	v_pk_mul_f32 v[46:47], v[14:15], v[14:15]
	v_pk_mul_f32 v[48:49], v[10:11], v[10:11]
	v_mov_b32_e32 v54, v50
	v_mov_b32_e32 v55, v52
	v_mov_b32_e32 v52, v51
	v_pk_add_f32 v[50:51], v[54:55], v[52:53]
	v_mov_b32_e32 v52, v46
	v_mov_b32_e32 v53, v48
	v_pk_mul_f32 v[42:43], v[0:1], v[0:1]
	v_pk_mul_f32 v[44:45], v[4:5], v[4:5]
	v_pk_add_f32 v[50:51], v[52:53], v[50:51]
	v_mov_b32_e32 v48, v47
	v_pk_mul_f32 v[16:17], v[2:3], v[2:3]
	v_pk_mul_f32 v[18:19], v[6:7], v[6:7]
	v_pk_add_f32 v[46:47], v[48:49], v[50:51]
	v_mov_b32_e32 v48, v42
	v_mov_b32_e32 v49, v44
	v_mov_b32_e32 v44, v43
	v_pk_add_f32 v[42:43], v[48:49], v[44:45]
	v_mov_b32_e32 v44, v16
	v_mov_b32_e32 v45, v18
	v_pk_add_f32 v[42:43], v[44:45], v[42:43]
	v_mov_b32_e32 v18, v17
	v_lshl_add_u64 v[40:41], v[40:41], 2, s[2:3]
	v_pk_add_f32 v[16:17], v[18:19], v[42:43]
	v_add_f32_e32 v18, v46, v47
	s_mov_b64 s[6:7], 0x1000
	v_add_f32_e32 v17, v17, v18
	v_lshl_add_u64 v[18:19], v[40:41], 0, s[6:7]
	v_lshl_add_u64 v[40:41], v[40:41], 0, v[96:97]
	v_lshl_add_u64 v[50:51], v[18:19], 0, v[96:97]
	global_load_dwordx4 v[42:45], v[28:29], off
	global_load_dwordx4 v[46:49], v[40:41], off
	v_add_f32_e32 v16, v16, v17
	global_load_dwordx4 v[50:53], v[50:51], off
	global_load_dwordx4 v[198:201], v[28:29], off offset:1024
	global_load_dwordx4 v[210:213], v[40:41], off offset:1024
	v_mov_b32_e32 v234, v32
	v_mov_b32_e32 v235, v97
	v_lshl_add_u64 v[234:235], v[18:19], 0, v[234:235]
	global_load_dwordx4 v[222:225], v[234:235], off
	global_load_dwordx4 v[202:205], v[28:29], off offset:2048
	global_load_dwordx4 v[214:217], v[40:41], off offset:2048
	v_mov_b32_e32 v236, v34
	v_mov_b32_e32 v237, v97
	v_lshl_add_u64 v[236:237], v[18:19], 0, v[236:237]
	global_load_dwordx4 v[226:229], v[236:237], off
	global_load_dwordx4 v[206:209], v[28:29], off offset:3072
	global_load_dwordx4 v[218:221], v[40:41], off offset:3072
	v_mov_b32_e32 v238, v36
	v_mov_b32_e32 v239, v97
	v_lshl_add_u64 v[238:239], v[18:19], 0, v[238:239]
	global_load_dwordx4 v[230:233], v[238:239], off
	ds_bpermute_b32 v17, v62, v16
	v_lshl_add_u64 v[38:39], v[38:39], 1, v[30:31]
	v_mov_b32_e32 v33, v97
	v_mov_b32_e32 v35, v97
	v_mov_b32_e32 v37, v97
	s_waitcnt lgkmcnt(0)
	v_add_f32_e32 v16, v16, v17
	ds_bpermute_b32 v17, v63, v16
	v_lshl_add_u64 v[20:21], v[20:21], 0, s[48:49]
	v_min_i32_e32 v116, 0x41ff, v20
	v_add_u32_e32 v116, 0xfffffe00, v116
	v_lshlrev_b32_e32 v116, 12, v116
	v_mov_b32_e32 v117, v97
	v_lshl_add_u64 v[116:117], s[84:85], 0, v[116:117]
	v_lshl_add_u64 v[116:117], v[116:117], 0, v[96:97]
	global_load_dwordx4 v[100:103], v[116:117], off
	global_load_dwordx4 v[104:107], v[116:117], off offset:1024
	global_load_dwordx4 v[108:111], v[116:117], off offset:2048
	global_load_dwordx4 v[112:115], v[116:117], off offset:3072
	s_movk_i32 s6, 0x41ff
	s_waitcnt lgkmcnt(0)
	v_add_f32_e32 v16, v16, v17
	ds_bpermute_b32 v17, v64, v16
	s_waitcnt lgkmcnt(0)
	v_add_f32_e32 v16, v16, v17
	ds_bpermute_b32 v17, v65, v16
	s_waitcnt lgkmcnt(0)
	v_add_f32_e32 v16, v16, v17
	ds_bpermute_b32 v17, v66, v16
	s_waitcnt lgkmcnt(0)
	v_add_f32_e32 v16, v16, v17
	ds_bpermute_b32 v17, v67, v16
	s_waitcnt lgkmcnt(0)
	v_add_f32_e32 v16, v16, v17
	v_mov_b32_e32 v17, 0x358637bd
	v_fmamk_f32 v16, v16, 0x3a800000, v17
	v_cmp_gt_f32_e32 vcc, s42, v16
	v_mul_f32_e32 v17, 0x4b800000, v16
	s_nop 0
	v_cndmask_b32_e32 v16, v16, v17, vcc
	v_rsq_f32_e32 v16, v16
	s_nop 0
	v_mul_f32_e32 v17, 0x45800000, v16
	v_cndmask_b32_e32 v16, v16, v17, vcc
	v_pk_mul_f32 v[14:15], v[14:15], v[16:17] op_sel_hi:[1,0]
	v_pk_mul_f32 v[12:13], v[12:13], v[16:17] op_sel_hi:[1,0]
	v_pk_mul_f32 v[10:11], v[10:11], v[16:17] op_sel_hi:[1,0]
	v_pk_mul_f32 v[8:9], v[8:9], v[16:17] op_sel_hi:[1,0]
	v_pk_mul_f32 v[6:7], v[6:7], v[16:17] op_sel_hi:[1,0]
	v_pk_mul_f32 v[4:5], v[4:5], v[16:17] op_sel_hi:[1,0]
	v_pk_mul_f32 v[2:3], v[2:3], v[16:17] op_sel_hi:[1,0]
	v_pk_mul_f32 v[0:1], v[0:1], v[16:17] op_sel_hi:[1,0]
	v_cmp_lt_i32_e32 vcc, s6, v20
	s_or_b64 s[4:5], vcc, s[4:5]
	s_waitcnt vmcnt(13)
	v_pk_mul_f32 v[12:13], v[42:43], v[12:13]
	v_pk_mul_f32 v[14:15], v[44:45], v[14:15]
	v_pk_add_f32 v[50:51], v[50:51], 1.0 op_sel_hi:[1,0]
	v_pk_add_f32 v[52:53], v[52:53], 1.0 op_sel_hi:[1,0]
	v_pk_fma_f32 v[12:13], v[50:51], v[12:13], v[46:47]
	v_pk_fma_f32 v[14:15], v[52:53], v[14:15], v[48:49]
	v_cvt_pk_bf16_f32 v12, v12, v13
	v_cvt_pk_bf16_f32 v13, v14, v15
	global_store_dwordx2 v[38:39], v[12:13], off
	s_waitcnt vmcnt(11)
	v_pk_mul_f32 v[8:9], v[198:199], v[8:9]
	v_pk_mul_f32 v[10:11], v[200:201], v[10:11]
	v_pk_add_f32 v[222:223], v[222:223], 1.0 op_sel_hi:[1,0]
	v_pk_add_f32 v[224:225], v[224:225], 1.0 op_sel_hi:[1,0]
	v_pk_fma_f32 v[8:9], v[222:223], v[8:9], v[210:211]
	v_pk_fma_f32 v[10:11], v[224:225], v[10:11], v[212:213]
	v_cvt_pk_bf16_f32 v8, v8, v9
	v_cvt_pk_bf16_f32 v9, v10, v11
	global_store_dwordx2 v[38:39], v[8:9], off offset:512
	s_waitcnt vmcnt(9)
	v_pk_mul_f32 v[4:5], v[202:203], v[4:5]
	v_pk_mul_f32 v[6:7], v[204:205], v[6:7]
	v_pk_add_f32 v[226:227], v[226:227], 1.0 op_sel_hi:[1,0]
	v_pk_add_f32 v[228:229], v[228:229], 1.0 op_sel_hi:[1,0]
	v_pk_fma_f32 v[4:5], v[226:227], v[4:5], v[214:215]
	v_pk_fma_f32 v[6:7], v[228:229], v[6:7], v[216:217]
	v_cvt_pk_bf16_f32 v4, v4, v5
	v_cvt_pk_bf16_f32 v5, v6, v7
	global_store_dwordx2 v[38:39], v[4:5], off offset:1024
	s_waitcnt vmcnt(7)
	v_pk_mul_f32 v[0:1], v[206:207], v[0:1]
	v_pk_mul_f32 v[2:3], v[208:209], v[2:3]
	v_pk_add_f32 v[230:231], v[230:231], 1.0 op_sel_hi:[1,0]
	v_pk_add_f32 v[232:233], v[232:233], 1.0 op_sel_hi:[1,0]
	v_pk_fma_f32 v[0:1], v[230:231], v[0:1], v[218:219]
	v_pk_fma_f32 v[2:3], v[232:233], v[2:3], v[220:221]
	v_cvt_pk_bf16_f32 v0, v0, v1
	v_cvt_pk_bf16_f32 v1, v2, v3
	global_store_dwordx2 v[38:39], v[0:1], off offset:1536
	s_andn2_b64 exec, exec, s[4:5]
	s_cbranch_execz .LBB0_1955
.LBB0_1953:
	v_cmp_gt_i32_e32 vcc, s96, v20
	v_mov_b32_e32 v0, 0xfffffe00
	v_mov_b32_e32 v1, 0x4000
	v_cndmask_b32_e32 v0, v0, v1, vcc
	v_add_u32_e32 v17, v0, v20
	v_add_u32_e32 v16, 0xffffc000, v17
	v_lshrrev_b32_e32 v2, 2, v16
	s_movk_i32 s6, 0x4000
	v_ashrrev_i32_e32 v1, 11, v17
	v_add_u32_e32 v2, 8, v2
	v_cmp_gt_i32_e64 s[6:7], s6, v17
	s_nop 1
	v_cndmask_b32_e64 v33, v2, v1, s[6:7]
	v_mov_b32_e32 v1, s13
	v_mov_b32_e32 v2, s85
	v_cndmask_b32_e64 v3, v1, v2, s[6:7]
	v_mov_b32_e32 v1, s12
	v_mov_b32_e32 v2, s84
	v_cndmask_b32_e64 v2, v1, v2, s[6:7]
	v_cndmask_b32_e64 v1, -1, 0, vcc
	v_lshl_add_u64 v[18:19], v[20:21], 0, v[0:1]
	v_lshlrev_b64 v[0:1], 12, v[18:19]
	v_lshl_add_u64 v[0:1], v[2:3], 0, v[0:1]
	v_lshl_add_u64 v[0:1], v[0:1], 0, v[96:97]
	s_cmp_lg_u32 s101, 0
	s_cbranch_scc1 .Lnp_pf_n1
	global_load_dwordx4 v[12:15], v[0:1], off
	global_load_dwordx4 v[8:11], v[0:1], off offset:1024
	global_load_dwordx4 v[4:7], v[0:1], off offset:2048
	s_nop 0
	global_load_dwordx4 v[0:3], v[0:1], off offset:3072
	s_branch .Lnp_go_n1

; DI void norm_phase(const float* xp, const float* xs, const float* gvec, const float* MODL  , int sc_off, bf16_t* H, int tid,
;                    const float* P, int nparts, const float* pgate, float* X) {
;     ...
;         if (row >= MP && nparts > 0) {
;             f32x4 s[4];
; #pragma unroll
;             for (int j = 0; j < 4; ++j) s[j] = (f32x4){0.f, 0.f, 0.f, 0.f};
;             for (int p = 0; p < nparts; ++p) { const float* pr = P + ((size_t)p * 512 + (row - MP)) * 1024 + 4 * lane;
; #pragma unroll
;                 for (int j = 0; j < 4; ++j) s[j] += *(const f32x4*)(pr + 256 * j); }
; #pragma unroll
;             for (int j = 0; j < 4; ++j) { v[j] += *(const f32x4*)(pgate + (size_t)bi * NMOD + 4 * lane + 256 * j) * s[j]; *(f32x4*)(X + (size_t)row * 1024 + 4 * lane + 256 * j) = v[j]; }
;         }
.Lnp_go_n1:
	s_mov_b32 s101, 1
	s_movk_i32 s6, 0x6000
	v_mad_i64_i32 v[40:41], s[6:7], v33, s6, 0
	s_movk_i32 s6, 0x3fff
	s_nop 0
	v_cmp_lt_i32_e32 vcc, s6, v17
	v_lshlrev_b64 v[38:39], 10, v[18:19]
	s_and_b64 s[8:9], s[10:11], vcc
	s_and_saveexec_b64 s[6:7], s[8:9]
	s_cbranch_execz .LBB0_1952
	v_mov_b32_e32 v17, v97
	v_lshlrev_b64 v[16:17], 12, v[16:17]
	v_lshl_add_u64 v[16:17], v[22:23], 0, v[16:17]
	v_mov_b64_e32 v[132:133], v[16:17]
	v_lshl_add_u64 v[164:165], v[40:41], 2, v[24:25]
	v_lshl_add_u64 v[178:179], v[38:39], 2, v[26:27]
	global_load_dwordx4 v[170:173], v[164:165], off
	global_load_dwordx4 v[174:177], v[164:165], off offset:1024
	global_load_dwordx4 v[190:193], v[164:165], off offset:2048
	global_load_dwordx4 v[250:253], v[164:165], off offset:3072
	global_load_dwordx4 v[198:201], v[132:133], off
	global_load_dwordx4 v[202:205], v[132:133], off offset:1024
	global_load_dwordx4 v[206:209], v[132:133], off offset:2048
	global_load_dwordx4 v[210:213], v[132:133], off offset:3072
	v_add_co_u32_e32 v132, vcc, 0x200000, v132
	s_nop 1
	v_addc_co_u32_e32 v133, vcc, 0, v133, vcc
	global_load_dwordx4 v[214:217], v[132:133], off
	global_load_dwordx4 v[218:221], v[132:133], off offset:1024
	global_load_dwordx4 v[222:225], v[132:133], off offset:2048
	global_load_dwordx4 v[226:229], v[132:133], off offset:3072
	v_add_co_u32_e32 v132, vcc, 0x200000, v132
	s_nop 1
	v_addc_co_u32_e32 v133, vcc, 0, v133, vcc
	global_load_dwordx4 v[230:233], v[132:133], off
	global_load_dwordx4 v[234:237], v[132:133], off offset:1024
	global_load_dwordx4 v[238:241], v[132:133], off offset:2048
	global_load_dwordx4 v[242:245], v[132:133], off offset:3072
	v_add_co_u32_e32 v132, vcc, 0x200000, v132
	s_nop 1
	v_addc_co_u32_e32 v133, vcc, 0, v133, vcc
	global_load_dwordx4 v[246:249], v[132:133], off
	global_load_dwordx4 v[148:151], v[132:133], off offset:1024
	global_load_dwordx4 v[152:155], v[132:133], off offset:2048
	global_load_dwordx4 v[156:159], v[132:133], off offset:3072
	v_add_co_u32_e32 v132, vcc, 0x200000, v132
	s_nop 1
	v_addc_co_u32_e32 v133, vcc, 0, v133, vcc
	global_load_dwordx4 v[160:163], v[132:133], off
	global_load_dwordx4 v[182:185], v[132:133], off offset:1024
	global_load_dwordx4 v[186:189], v[132:133], off offset:2048
	s_waitcnt vmcnt(18)
	v_pk_add_f32 v[126:127], v[200:201], 0 op_sel_hi:[1,0]
	v_pk_add_f32 v[124:125], v[198:199], 0 op_sel_hi:[1,0]
	global_load_dwordx4 v[198:201], v[132:133], off offset:3072
	s_waitcnt vmcnt(18)
	v_pk_add_f32 v[130:131], v[204:205], 0 op_sel_hi:[1,0]
	v_pk_add_f32 v[128:129], v[202:203], 0 op_sel_hi:[1,0]
	v_add_co_u32_e32 v132, vcc, 0x200000, v132
	s_nop 1
	v_addc_co_u32_e32 v133, vcc, 0, v133, vcc
	global_load_dwordx4 v[202:205], v[132:133], off
	s_waitcnt vmcnt(18)
	v_pk_add_f32 v[140:141], v[208:209], 0 op_sel_hi:[1,0]
	v_pk_add_f32 v[138:139], v[206:207], 0 op_sel_hi:[1,0]
	global_load_dwordx4 v[206:209], v[132:133], off offset:1024
	s_waitcnt vmcnt(18)
	v_pk_add_f32 v[144:145], v[212:213], 0 op_sel_hi:[1,0]
	v_pk_add_f32 v[142:143], v[210:211], 0 op_sel_hi:[1,0]
	global_load_dwordx4 v[210:213], v[132:133], off offset:2048
	s_waitcnt vmcnt(18)
	v_pk_add_f32 v[126:127], v[126:127], v[216:217]
	v_pk_add_f32 v[124:125], v[124:125], v[214:215]
	global_load_dwordx4 v[214:217], v[132:133], off offset:3072
	s_waitcnt vmcnt(18)
	v_pk_add_f32 v[130:131], v[130:131], v[220:221]
	v_pk_add_f32 v[128:129], v[128:129], v[218:219]
	v_add_co_u32_e32 v132, vcc, 0x200000, v132
	s_nop 1
	v_addc_co_u32_e32 v133, vcc, 0, v133, vcc
	global_load_dwordx4 v[218:221], v[132:133], off
	s_waitcnt vmcnt(18)
	v_pk_add_f32 v[140:141], v[140:141], v[224:225]
	v_pk_add_f32 v[138:139], v[138:139], v[222:223]
	global_load_dwordx4 v[222:225], v[132:133], off offset:1024
	s_waitcnt vmcnt(18)
	v_pk_add_f32 v[144:145], v[144:145], v[228:229]
	v_pk_add_f32 v[142:143], v[142:143], v[226:227]
	global_load_dwordx4 v[226:229], v[132:133], off offset:2048
	s_waitcnt vmcnt(18)
	v_pk_add_f32 v[126:127], v[126:127], v[232:233]
	v_pk_add_f32 v[124:125], v[124:125], v[230:231]
	global_load_dwordx4 v[230:233], v[132:133], off offset:3072
	s_waitcnt vmcnt(18)
	v_pk_add_f32 v[130:131], v[130:131], v[236:237]
	v_pk_add_f32 v[128:129], v[128:129], v[234:235]
	v_add_co_u32_e32 v132, vcc, 0x200000, v132
	s_nop 1
	v_addc_co_u32_e32 v133, vcc, 0, v133, vcc
	global_load_dwordx4 v[234:237], v[132:133], off
	s_waitcnt vmcnt(18)
	v_pk_add_f32 v[140:141], v[140:141], v[240:241]
	v_pk_add_f32 v[138:139], v[138:139], v[238:239]
	global_load_dwordx4 v[238:241], v[132:133], off offset:1024
	s_waitcnt vmcnt(18)
	v_pk_add_f32 v[144:145], v[144:145], v[244:245]
	v_pk_add_f32 v[142:143], v[142:143], v[242:243]
	global_load_dwordx4 v[242:245], v[132:133], off offset:2048
	s_waitcnt vmcnt(18)
	v_pk_add_f32 v[126:127], v[126:127], v[248:249]
	v_pk_add_f32 v[124:125], v[124:125], v[246:247]
	global_load_dwordx4 v[246:249], v[132:133], off offset:3072
	s_waitcnt vmcnt(18)
	v_pk_add_f32 v[130:131], v[130:131], v[150:151]
	v_pk_add_f32 v[128:129], v[128:129], v[148:149]
	v_add_co_u32_e32 v132, vcc, 0x200000, v132
	s_nop 1
	v_addc_co_u32_e32 v133, vcc, 0, v133, vcc
	global_load_dwordx4 v[148:151], v[132:133], off
	s_waitcnt vmcnt(18)
	v_pk_add_f32 v[140:141], v[140:141], v[154:155]
	v_pk_add_f32 v[138:139], v[138:139], v[152:153]
	global_load_dwordx4 v[152:155], v[132:133], off offset:1024
	s_waitcnt vmcnt(18)
	v_pk_add_f32 v[144:145], v[144:145], v[158:159]
	v_pk_add_f32 v[142:143], v[142:143], v[156:157]
	global_load_dwordx4 v[156:159], v[132:133], off offset:2048
	s_waitcnt vmcnt(18)
	v_pk_add_f32 v[126:127], v[126:127], v[162:163]
	v_pk_add_f32 v[124:125], v[124:125], v[160:161]
	global_load_dwordx4 v[160:163], v[132:133], off offset:3072
	s_waitcnt vmcnt(18)
; DI void norm_phase(const float* xp, const float* xs, const float* gvec, const float* MODL  , int sc_off, bf16_t* H, int tid,
;                    const float* P, int nparts, const float* pgate, float* X) {
;     ...
;         if (row >= MP && nparts > 0) {
;             f32x4 s[4];
; #pragma unroll
;             for (int j = 0; j < 4; ++j) s[j] = (f32x4){0.f, 0.f, 0.f, 0.f};
;             for (int p = 0; p < nparts; ++p) { const float* pr = P + ((size_t)p * 512 + (row - MP)) * 1024 + 4 * lane;
; #pragma unroll
;                 for (int j = 0; j < 4; ++j) s[j] += *(const f32x4*)(pr + 256 * j); }
; #pragma unroll
;             for (int j = 0; j < 4; ++j) { v[j] += *(const f32x4*)(pgate + (size_t)bi * NMOD + 4 * lane + 256 * j) * s[j]; *(f32x4*)(X + (size_t)row * 1024 + 4 * lane + 256 * j) = v[j]; }
;         }
	v_pk_add_f32 v[130:131], v[130:131], v[184:185]
	v_pk_add_f32 v[128:129], v[128:129], v[182:183]
	v_add_co_u32_e32 v132, vcc, 0x200000, v132
	s_nop 1
	v_addc_co_u32_e32 v133, vcc, 0, v133, vcc
	global_load_dwordx4 v[182:185], v[132:133], off
	s_waitcnt vmcnt(18)
	v_pk_add_f32 v[140:141], v[140:141], v[188:189]
	v_pk_add_f32 v[138:139], v[138:139], v[186:187]
	global_load_dwordx4 v[186:189], v[132:133], off offset:1024
	s_waitcnt vmcnt(18)
	v_pk_add_f32 v[144:145], v[144:145], v[200:201]
	v_pk_add_f32 v[142:143], v[142:143], v[198:199]
	global_load_dwordx4 v[198:201], v[132:133], off offset:2048
	s_waitcnt vmcnt(18)
	v_pk_add_f32 v[126:127], v[126:127], v[204:205]
	v_pk_add_f32 v[124:125], v[124:125], v[202:203]
	global_load_dwordx4 v[202:205], v[132:133], off offset:3072
	s_waitcnt vmcnt(18)
	v_pk_add_f32 v[130:131], v[130:131], v[208:209]
	v_pk_add_f32 v[128:129], v[128:129], v[206:207]
	v_add_co_u32_e32 v132, vcc, 0x200000, v132
	s_nop 1
	v_addc_co_u32_e32 v133, vcc, 0, v133, vcc
	global_load_dwordx4 v[206:209], v[132:133], off
	s_waitcnt vmcnt(18)
	v_pk_add_f32 v[140:141], v[140:141], v[212:213]
	v_pk_add_f32 v[138:139], v[138:139], v[210:211]
	global_load_dwordx4 v[210:213], v[132:133], off offset:1024
	s_waitcnt vmcnt(18)
	v_pk_add_f32 v[144:145], v[144:145], v[216:217]
	v_pk_add_f32 v[142:143], v[142:143], v[214:215]
	global_load_dwordx4 v[214:217], v[132:133], off offset:2048
	s_waitcnt vmcnt(18)
	v_pk_add_f32 v[126:127], v[126:127], v[220:221]
	v_pk_add_f32 v[124:125], v[124:125], v[218:219]
	global_load_dwordx4 v[218:221], v[132:133], off offset:3072
	s_waitcnt vmcnt(18)
	v_pk_add_f32 v[130:131], v[130:131], v[224:225]
	v_pk_add_f32 v[128:129], v[128:129], v[222:223]
	v_add_co_u32_e32 v132, vcc, 0x200000, v132
	s_nop 1
	v_addc_co_u32_e32 v133, vcc, 0, v133, vcc
	global_load_dwordx4 v[222:225], v[132:133], off
	s_waitcnt vmcnt(18)
	v_pk_add_f32 v[140:141], v[140:141], v[228:229]
	v_pk_add_f32 v[138:139], v[138:139], v[226:227]
	global_load_dwordx4 v[226:229], v[132:133], off offset:1024
	s_waitcnt vmcnt(18)
	v_pk_add_f32 v[144:145], v[144:145], v[232:233]
	v_pk_add_f32 v[142:143], v[142:143], v[230:231]
	global_load_dwordx4 v[230:233], v[132:133], off offset:2048
	s_waitcnt vmcnt(18)
	v_pk_add_f32 v[126:127], v[126:127], v[236:237]
	v_pk_add_f32 v[124:125], v[124:125], v[234:235]
	global_load_dwordx4 v[234:237], v[132:133], off offset:3072
	s_waitcnt vmcnt(18)
	v_pk_add_f32 v[130:131], v[130:131], v[240:241]
	v_pk_add_f32 v[128:129], v[128:129], v[238:239]
	v_add_co_u32_e32 v132, vcc, 0x200000, v132
	s_nop 1
	v_addc_co_u32_e32 v133, vcc, 0, v133, vcc
	global_load_dwordx4 v[238:241], v[132:133], off
	s_waitcnt vmcnt(18)
	v_pk_add_f32 v[140:141], v[140:141], v[244:245]
	v_pk_add_f32 v[138:139], v[138:139], v[242:243]
	global_load_dwordx4 v[242:245], v[132:133], off offset:1024
	s_waitcnt vmcnt(18)
	v_pk_add_f32 v[144:145], v[144:145], v[248:249]
	v_pk_add_f32 v[142:143], v[142:143], v[246:247]
	global_load_dwordx4 v[246:249], v[132:133], off offset:2048
	s_waitcnt vmcnt(18)
	v_pk_add_f32 v[126:127], v[126:127], v[150:151]
	v_pk_add_f32 v[124:125], v[124:125], v[148:149]
	global_load_dwordx4 v[148:151], v[132:133], off offset:3072
	s_waitcnt vmcnt(18)
	v_pk_add_f32 v[130:131], v[130:131], v[154:155]
	v_pk_add_f32 v[128:129], v[128:129], v[152:153]
	v_add_co_u32_e32 v132, vcc, 0x200000, v132
	s_nop 1
	v_addc_co_u32_e32 v133, vcc, 0, v133, vcc
	global_load_dwordx4 v[152:155], v[132:133], off
	s_waitcnt vmcnt(18)
	v_pk_add_f32 v[140:141], v[140:141], v[158:159]
	v_pk_add_f32 v[138:139], v[138:139], v[156:157]
	global_load_dwordx4 v[156:159], v[132:133], off offset:1024
	s_waitcnt vmcnt(18)
	v_pk_add_f32 v[144:145], v[144:145], v[162:163]
	v_pk_add_f32 v[142:143], v[142:143], v[160:161]
	global_load_dwordx4 v[160:163], v[132:133], off offset:2048
	s_waitcnt vmcnt(18)
	v_pk_add_f32 v[126:127], v[126:127], v[184:185]
	v_pk_add_f32 v[124:125], v[124:125], v[182:183]
	global_load_dwordx4 v[182:185], v[132:133], off offset:3072
	s_waitcnt vmcnt(18)
	v_pk_add_f32 v[130:131], v[130:131], v[188:189]
	v_pk_add_f32 v[128:129], v[128:129], v[186:187]
	v_add_co_u32_e32 v132, vcc, 0x200000, v132
	s_nop 1
	v_addc_co_u32_e32 v133, vcc, 0, v133, vcc
	global_load_dwordx4 v[186:189], v[132:133], off
	s_waitcnt vmcnt(18)
	v_pk_add_f32 v[140:141], v[140:141], v[200:201]
	v_pk_add_f32 v[138:139], v[138:139], v[198:199]
	global_load_dwordx4 v[198:201], v[132:133], off offset:1024
	s_waitcnt vmcnt(18)
	v_pk_add_f32 v[144:145], v[144:145], v[204:205]
	v_pk_add_f32 v[142:143], v[142:143], v[202:203]
	global_load_dwordx4 v[202:205], v[132:133], off offset:2048
	s_waitcnt vmcnt(18)
	v_pk_add_f32 v[126:127], v[126:127], v[208:209]
	v_pk_add_f32 v[124:125], v[124:125], v[206:207]
	global_load_dwordx4 v[206:209], v[132:133], off offset:3072
	s_waitcnt vmcnt(18)
	v_pk_add_f32 v[130:131], v[130:131], v[212:213]
	v_pk_add_f32 v[128:129], v[128:129], v[210:211]
	v_add_co_u32_e32 v132, vcc, 0x200000, v132
	s_nop 1
	v_addc_co_u32_e32 v133, vcc, 0, v133, vcc
	global_load_dwordx4 v[210:213], v[132:133], off
	s_waitcnt vmcnt(18)
	v_pk_add_f32 v[140:141], v[140:141], v[216:217]
	v_pk_add_f32 v[138:139], v[138:139], v[214:215]
	global_load_dwordx4 v[214:217], v[132:133], off offset:1024
	s_waitcnt vmcnt(18)
	v_pk_add_f32 v[144:145], v[144:145], v[220:221]
	v_pk_add_f32 v[142:143], v[142:143], v[218:219]
	global_load_dwordx4 v[218:221], v[132:133], off offset:2048
	s_waitcnt vmcnt(18)
	v_pk_add_f32 v[126:127], v[126:127], v[224:225]
	v_pk_add_f32 v[124:125], v[124:125], v[222:223]
	global_load_dwordx4 v[222:225], v[132:133], off offset:3072
	s_waitcnt vmcnt(18)
; DI void norm_phase(const float* xp, const float* xs, const float* gvec, const float* MODL  , int sc_off, bf16_t* H, int tid,
;                    const float* P, int nparts, const float* pgate, float* X) {
;     ...
;         if (row >= MP && nparts > 0) {
;             f32x4 s[4];
; #pragma unroll
;             for (int j = 0; j < 4; ++j) s[j] = (f32x4){0.f, 0.f, 0.f, 0.f};
;             for (int p = 0; p < nparts; ++p) { const float* pr = P + ((size_t)p * 512 + (row - MP)) * 1024 + 4 * lane;
; #pragma unroll
;                 for (int j = 0; j < 4; ++j) s[j] += *(const f32x4*)(pr + 256 * j); }
; #pragma unroll
;             for (int j = 0; j < 4; ++j) { v[j] += *(const f32x4*)(pgate + (size_t)bi * NMOD + 4 * lane + 256 * j) * s[j]; *(f32x4*)(X + (size_t)row * 1024 + 4 * lane + 256 * j) = v[j]; }
;         }
	v_pk_add_f32 v[130:131], v[130:131], v[228:229]
	v_pk_add_f32 v[128:129], v[128:129], v[226:227]
	v_add_co_u32_e32 v132, vcc, 0x200000, v132
	s_nop 1
	v_addc_co_u32_e32 v133, vcc, 0, v133, vcc
	global_load_dwordx4 v[226:229], v[132:133], off
	s_waitcnt vmcnt(18)
	v_pk_add_f32 v[140:141], v[140:141], v[232:233]
	v_pk_add_f32 v[138:139], v[138:139], v[230:231]
	global_load_dwordx4 v[230:233], v[132:133], off offset:1024
	s_waitcnt vmcnt(18)
	v_pk_add_f32 v[144:145], v[144:145], v[236:237]
	v_pk_add_f32 v[142:143], v[142:143], v[234:235]
	global_load_dwordx4 v[234:237], v[132:133], off offset:2048
	s_waitcnt vmcnt(18)
	v_pk_add_f32 v[126:127], v[126:127], v[240:241]
	v_pk_add_f32 v[124:125], v[124:125], v[238:239]
	global_load_dwordx4 v[238:241], v[132:133], off offset:3072
	s_waitcnt vmcnt(18)
	v_pk_add_f32 v[130:131], v[130:131], v[244:245]
	v_pk_add_f32 v[128:129], v[128:129], v[242:243]
	v_add_co_u32_e32 v132, vcc, 0x200000, v132
	s_nop 1
	v_addc_co_u32_e32 v133, vcc, 0, v133, vcc
	global_load_dwordx4 v[242:245], v[132:133], off
	s_waitcnt vmcnt(18)
	v_pk_add_f32 v[140:141], v[140:141], v[248:249]
	v_pk_add_f32 v[138:139], v[138:139], v[246:247]
	global_load_dwordx4 v[246:249], v[132:133], off offset:1024
	s_waitcnt vmcnt(18)
	v_pk_add_f32 v[144:145], v[144:145], v[150:151]
	v_pk_add_f32 v[142:143], v[142:143], v[148:149]
	global_load_dwordx4 v[148:151], v[132:133], off offset:2048
	s_waitcnt vmcnt(18)
	v_pk_add_f32 v[126:127], v[126:127], v[154:155]
	v_pk_add_f32 v[124:125], v[124:125], v[152:153]
	global_load_dwordx4 v[152:155], v[132:133], off offset:3072
	s_waitcnt vmcnt(18)
	v_pk_add_f32 v[130:131], v[130:131], v[158:159]
	v_pk_add_f32 v[128:129], v[128:129], v[156:157]
	v_add_co_u32_e32 v132, vcc, 0x200000, v132
	s_nop 1
	v_addc_co_u32_e32 v133, vcc, 0, v133, vcc
	global_load_dwordx4 v[156:159], v[132:133], off
	s_waitcnt vmcnt(18)
	v_pk_add_f32 v[140:141], v[140:141], v[162:163]
	v_pk_add_f32 v[138:139], v[138:139], v[160:161]
	global_load_dwordx4 v[160:163], v[132:133], off offset:1024
	s_waitcnt vmcnt(18)
	v_pk_add_f32 v[144:145], v[144:145], v[184:185]
	v_pk_add_f32 v[142:143], v[142:143], v[182:183]
	global_load_dwordx4 v[182:185], v[132:133], off offset:2048
	s_waitcnt vmcnt(18)
	v_pk_add_f32 v[126:127], v[126:127], v[188:189]
	v_pk_add_f32 v[124:125], v[124:125], v[186:187]
	global_load_dwordx4 v[186:189], v[132:133], off offset:3072
	s_waitcnt vmcnt(18)
	v_pk_add_f32 v[130:131], v[130:131], v[200:201]
	v_pk_add_f32 v[128:129], v[128:129], v[198:199]
	v_add_co_u32_e32 v132, vcc, 0x200000, v132
	s_nop 1
	v_addc_co_u32_e32 v133, vcc, 0, v133, vcc
	global_load_dwordx4 v[198:201], v[132:133], off
	s_waitcnt vmcnt(18)
	v_pk_add_f32 v[140:141], v[140:141], v[204:205]
	v_pk_add_f32 v[138:139], v[138:139], v[202:203]
	global_load_dwordx4 v[202:205], v[132:133], off offset:1024
	s_waitcnt vmcnt(18)
	v_pk_add_f32 v[144:145], v[144:145], v[208:209]
	v_pk_add_f32 v[142:143], v[142:143], v[206:207]
	global_load_dwordx4 v[206:209], v[132:133], off offset:2048
	s_waitcnt vmcnt(18)
	v_pk_add_f32 v[126:127], v[126:127], v[212:213]
	v_pk_add_f32 v[124:125], v[124:125], v[210:211]
	global_load_dwordx4 v[210:213], v[132:133], off offset:3072
	s_waitcnt vmcnt(18)
	v_pk_add_f32 v[130:131], v[130:131], v[216:217]
	v_pk_add_f32 v[128:129], v[128:129], v[214:215]
	v_add_co_u32_e32 v132, vcc, 0x200000, v132
	s_nop 1
	v_addc_co_u32_e32 v133, vcc, 0, v133, vcc
	global_load_dwordx4 v[214:217], v[132:133], off
	s_waitcnt vmcnt(18)
	v_pk_add_f32 v[140:141], v[140:141], v[220:221]
	v_pk_add_f32 v[138:139], v[138:139], v[218:219]
	global_load_dwordx4 v[218:221], v[132:133], off offset:1024
	s_waitcnt vmcnt(18)
	v_pk_add_f32 v[144:145], v[144:145], v[224:225]
	v_pk_add_f32 v[142:143], v[142:143], v[222:223]
	global_load_dwordx4 v[222:225], v[132:133], off offset:2048
	s_waitcnt vmcnt(18)
; DI void norm_phase(const float* xp, const float* xs, const float* gvec, const float* MODL  , int sc_off, bf16_t* H, int tid,
;                    const float* P, int nparts, const float* pgate, float* X) {
;     ...
;         if (row >= MP && nparts > 0) {
;             f32x4 s[4];
; #pragma unroll
;             for (int j = 0; j < 4; ++j) s[j] = (f32x4){0.f, 0.f, 0.f, 0.f};
;             for (int p = 0; p < nparts; ++p) { const float* pr = P + ((size_t)p * 512 + (row - MP)) * 1024 + 4 * lane;
; #pragma unroll
;                 for (int j = 0; j < 4; ++j) s[j] += *(const f32x4*)(pr + 256 * j); }
; #pragma unroll
;             for (int j = 0; j < 4; ++j) { v[j] += *(const f32x4*)(pgate + (size_t)bi * NMOD + 4 * lane + 256 * j) * s[j]; *(f32x4*)(X + (size_t)row * 1024 + 4 * lane + 256 * j) = v[j]; }
;         }
	v_pk_add_f32 v[126:127], v[126:127], v[228:229]
	v_pk_add_f32 v[124:125], v[124:125], v[226:227]
	global_load_dwordx4 v[226:229], v[132:133], off offset:3072
	s_waitcnt vmcnt(18)
	v_pk_add_f32 v[130:131], v[130:131], v[232:233]
	v_pk_add_f32 v[128:129], v[128:129], v[230:231]
	v_add_co_u32_e32 v132, vcc, 0x200000, v132
	s_nop 1
	v_addc_co_u32_e32 v133, vcc, 0, v133, vcc
	global_load_dwordx4 v[230:233], v[132:133], off
	s_waitcnt vmcnt(18)
	v_pk_add_f32 v[140:141], v[140:141], v[236:237]
	v_pk_add_f32 v[138:139], v[138:139], v[234:235]
	global_load_dwordx4 v[234:237], v[132:133], off offset:1024
	s_waitcnt vmcnt(18)
	v_pk_add_f32 v[144:145], v[144:145], v[240:241]
	v_pk_add_f32 v[142:143], v[142:143], v[238:239]
	global_load_dwordx4 v[238:241], v[132:133], off offset:2048
	s_waitcnt vmcnt(18)
	v_pk_add_f32 v[126:127], v[126:127], v[244:245]
	v_pk_add_f32 v[124:125], v[124:125], v[242:243]
	global_load_dwordx4 v[242:245], v[132:133], off offset:3072
	s_waitcnt vmcnt(18)
	v_pk_add_f32 v[130:131], v[130:131], v[248:249]
	v_pk_add_f32 v[128:129], v[128:129], v[246:247]
	s_waitcnt vmcnt(17)
	v_pk_add_f32 v[140:141], v[140:141], v[150:151]
	v_pk_add_f32 v[138:139], v[138:139], v[148:149]
	s_waitcnt vmcnt(16)
	v_pk_add_f32 v[144:145], v[144:145], v[154:155]
	v_pk_add_f32 v[142:143], v[142:143], v[152:153]
	s_waitcnt vmcnt(15)
	v_pk_add_f32 v[126:127], v[126:127], v[158:159]
	v_pk_add_f32 v[124:125], v[124:125], v[156:157]
	s_waitcnt vmcnt(14)
	v_pk_add_f32 v[130:131], v[130:131], v[162:163]
	v_pk_add_f32 v[128:129], v[128:129], v[160:161]
	s_waitcnt vmcnt(13)
	v_pk_add_f32 v[140:141], v[140:141], v[184:185]
	v_pk_add_f32 v[138:139], v[138:139], v[182:183]
	s_waitcnt vmcnt(12)
	v_pk_add_f32 v[144:145], v[144:145], v[188:189]
	v_pk_add_f32 v[142:143], v[142:143], v[186:187]
	s_waitcnt vmcnt(11)
	v_pk_add_f32 v[126:127], v[126:127], v[200:201]
	v_pk_add_f32 v[124:125], v[124:125], v[198:199]
	s_waitcnt vmcnt(10)
	v_pk_add_f32 v[130:131], v[130:131], v[204:205]
	v_pk_add_f32 v[128:129], v[128:129], v[202:203]
	s_waitcnt vmcnt(9)
	v_pk_add_f32 v[140:141], v[140:141], v[208:209]
	v_pk_add_f32 v[138:139], v[138:139], v[206:207]
	s_waitcnt vmcnt(8)
	v_pk_add_f32 v[144:145], v[144:145], v[212:213]
	v_pk_add_f32 v[142:143], v[142:143], v[210:211]
	s_waitcnt vmcnt(7)
	v_pk_add_f32 v[126:127], v[126:127], v[216:217]
	v_pk_add_f32 v[124:125], v[124:125], v[214:215]
	s_waitcnt vmcnt(6)
	v_pk_add_f32 v[130:131], v[130:131], v[220:221]
	v_pk_add_f32 v[128:129], v[128:129], v[218:219]
	s_waitcnt vmcnt(5)
	v_pk_add_f32 v[140:141], v[140:141], v[224:225]
	v_pk_add_f32 v[138:139], v[138:139], v[222:223]
	s_waitcnt vmcnt(4)
	v_pk_add_f32 v[144:145], v[144:145], v[228:229]
	v_pk_add_f32 v[142:143], v[142:143], v[226:227]
	s_waitcnt vmcnt(3)
	v_pk_add_f32 v[126:127], v[126:127], v[232:233]
	v_pk_add_f32 v[124:125], v[124:125], v[230:231]
	s_waitcnt vmcnt(2)
	v_pk_add_f32 v[130:131], v[130:131], v[236:237]
	v_pk_add_f32 v[128:129], v[128:129], v[234:235]
	s_waitcnt vmcnt(1)
	v_pk_add_f32 v[140:141], v[140:141], v[240:241]
	v_pk_add_f32 v[138:139], v[138:139], v[238:239]
	s_waitcnt vmcnt(0)
	v_pk_add_f32 v[144:145], v[144:145], v[244:245]
	v_pk_add_f32 v[142:143], v[142:143], v[242:243]
	v_pk_fma_f32 v[14:15], v[126:127], v[172:173], v[14:15]
	v_pk_fma_f32 v[12:13], v[124:125], v[170:171], v[12:13]
	global_store_dwordx4 v[178:179], v[12:15], off
	v_pk_fma_f32 v[10:11], v[130:131], v[176:177], v[10:11]
	v_pk_fma_f32 v[8:9], v[128:129], v[174:175], v[8:9]
	global_store_dwordx4 v[178:179], v[8:11], off offset:1024
	v_pk_fma_f32 v[6:7], v[140:141], v[192:193], v[6:7]
	v_pk_fma_f32 v[4:5], v[138:139], v[190:191], v[4:5]
	global_store_dwordx4 v[178:179], v[4:7], off offset:2048
	v_pk_fma_f32 v[2:3], v[144:145], v[252:253], v[2:3]
	v_pk_fma_f32 v[0:1], v[142:143], v[250:251], v[0:1]
	global_store_dwordx4 v[178:179], v[0:3], off offset:3072
	s_branch .LBB0_1952
